# layer-0 norm phase: the five late scale/shift loads issued with the row loads (one memory round trip per 4-row group instead of two)
# baseline (speedup 1.0000x reference)
.LBB0_492:
	s_add_i32 s4, s2, -3
	s_add_i32 s0, s2, 0xffff7ffd
	s_ashr_i32 s5, s4, 31
	s_cmpk_lt_i32 s14, 0x2000
	s_mov_b32 s8, 0x358637bd
	s_cselect_b32 s1, s5, 0
	s_cselect_b32 s0, s4, s0
	v_mov_b64_e32 v[92:93], s[8:9]
	s_cselect_b32 s3, s65, s69
	s_cselect_b32 s8, s64, s68
	s_lshl_b64 s[0:1], s[0:1], 12
	s_add_u32 s0, s8, s0
	s_addc_u32 s1, s3, s1
	s_add_i32 s8, s2, -2
	global_load_dwordx4 v[36:39], v[90:91], off
	global_load_dwordx4 v[40:43], v[90:91], off offset:1024
	global_load_dwordx4 v[76:79], v[90:91], off offset:2048
	global_load_dwordx4 v[80:83], v[90:91], off offset:3072
	s_add_i32 s3, s2, 0xffff7ffe
	global_load_dwordx4 v[56:59], v120, s[0:1]
	global_load_dwordx4 v[48:51], v120, s[0:1] offset:1024
	global_load_dwordx4 v[44:47], v120, s[0:1] offset:3072
	global_load_dwordx4 v[52:55], v120, s[0:1] offset:2048
	s_ashr_i32 s9, s8, 31
	s_cmp_lt_i32 s8, 0x8000
	s_cselect_b32 s1, s9, 0
	s_cselect_b32 s0, s8, s3
	s_cselect_b32 s3, s65, s69
	s_cselect_b32 s10, s64, s68
	s_lshl_b64 s[0:1], s[0:1], 12
	s_add_u32 s0, s10, s0
	s_addc_u32 s1, s3, s1
	s_add_i32 s10, s2, -1
	s_add_i32 s3, s2, 0xffff7fff
	global_load_dwordx4 v[72:75], v120, s[0:1]
	global_load_dwordx4 v[64:67], v120, s[0:1] offset:1024
	global_load_dwordx4 v[60:63], v120, s[0:1] offset:3072
	global_load_dwordx4 v[68:71], v120, s[0:1] offset:2048
	s_ashr_i32 s11, s10, 31
	s_cmp_lt_i32 s10, 0x8000
	s_cselect_b32 s1, s11, 0
	s_cselect_b32 s0, s10, s3
	s_cselect_b32 s3, s65, s69
	s_cselect_b32 s12, s64, s68
	s_lshl_b64 s[0:1], s[0:1], 12
	s_add_u32 s0, s12, s0
	s_addc_u32 s1, s3, s1
	global_load_dwordx4 v[12:15], v120, s[0:1]
	global_load_dwordx4 v[8:11], v120, s[0:1] offset:1024
	global_load_dwordx4 v[4:7], v120, s[0:1] offset:2048
	global_load_dwordx4 v[0:3], v120, s[0:1] offset:3072
	s_ashr_i32 s3, s2, 31
	s_add_i32 s12, s2, 0xffff8000
	s_cmp_lt_i32 s2, 0x8000
	s_cselect_b32 s1, s3, 0
	s_cselect_b32 s0, s2, s12
	s_cselect_b32 s12, s65, s69
	s_cselect_b32 s13, s64, s68
	s_lshl_b64 s[0:1], s[0:1], 12
	s_add_u32 s0, s13, s0
	s_addc_u32 s1, s12, s1
	s_min_i32 s12, s14, 0x2000
	global_load_dwordx4 v[28:31], v120, s[0:1]
	global_load_dwordx4 v[24:27], v120, s[0:1] offset:1024
	global_load_dwordx4 v[20:23], v120, s[0:1] offset:2048
	global_load_dwordx4 v[16:19], v120, s[0:1] offset:3072
	s_ashr_i32 s0, s12, 9
	s_mul_hi_i32 s1, s0, 0x6000
	s_mulk_i32 s0, 0x6000
	s_add_u32 s12, s34, s0
	s_addc_u32 s13, s35, s1
	s_add_u32 s0, s12, 0x1000
	s_addc_u32 s1, s13, 0
	global_load_dwordx4 v[32:35], v121, s[0:1]
	global_load_dwordx4 v[104:107], v122, s[0:1]
	global_load_dwordx4 v[126:129], v123, s[0:1]
	global_load_dwordx4 v[130:133], v124, s[0:1]
	global_load_dwordx4 v[134:137], v121, s[12:13]
	global_load_dwordx4 v[138:141], v121, s[12:13] offset:1024
	global_load_dwordx4 v[142:145], v121, s[12:13] offset:2048
	global_load_dwordx4 v[146:149], v121, s[12:13] offset:3072
	s_lshl_b64 s[8:9], s[8:9], 11
	s_add_i32 s14, s14, s29
	s_waitcnt vmcnt(0)
	v_pk_mul_f32 v[84:85], v[58:59], v[58:59]
	v_pk_mul_f32 v[86:87], v[56:57], v[56:57]
	v_pk_mul_f32 v[94:95], v[50:51], v[50:51]
	v_pk_mul_f32 v[96:97], v[48:49], v[48:49]
	v_pk_mov_b32 v[98:99], v[86:87], v[84:85] op_sel:[1,0]
	v_mov_b32_e32 v87, v85
	v_pk_mov_b32 v[84:85], v[96:97], v[94:95] op_sel:[1,0]
	v_mov_b32_e32 v97, v95
	v_mul_f32_e32 v94, v53, v53
	v_pk_add_f32 v[86:87], v[98:99], v[86:87]
	v_mul_f32_e32 v98, v55, v55
	v_pk_add_f32 v[84:85], v[84:85], v[96:97]
	v_mul_f32_e32 v100, v44, v44
	v_mul_f32_e32 v101, v45, v45
	v_mul_f32_e32 v102, v46, v46
	v_mul_f32_e32 v103, v47, v47
	v_pk_fma_f32 v[94:95], v[52:53], v[52:53], v[94:95] op_sel_hi:[1,1,0]
	v_pk_fma_f32 v[98:99], v[54:55], v[54:55], v[98:99] op_sel_hi:[1,1,0]
	v_pk_add_f32 v[86:87], v[86:87], v[86:87] op_sel:[0,1] op_sel_hi:[1,0]
	v_pk_add_f32 v[84:85], v[84:85], v[84:85] op_sel:[0,1] op_sel_hi:[1,0]
	v_mov_b32_e32 v95, v102
	v_mov_b32_e32 v99, v103
	v_mov_b32_e32 v87, v100
	v_mov_b32_e32 v85, v101
	v_pk_add_f32 v[94:95], v[94:95], v[98:99]
	v_pk_add_f32 v[84:85], v[86:87], v[84:85]
	v_pk_mul_f32 v[86:87], v[72:73], v[72:73]
	v_pk_add_f32 v[94:95], v[84:85], v[94:95]
	v_pk_mul_f32 v[84:85], v[74:75], v[74:75]
	v_pk_mul_f32 v[96:97], v[66:67], v[66:67]
	v_pk_mul_f32 v[98:99], v[64:65], v[64:65]
	v_pk_mov_b32 v[100:101], v[86:87], v[84:85] op_sel:[1,0]
	v_mov_b32_e32 v87, v85
	v_pk_mov_b32 v[84:85], v[98:99], v[96:97] op_sel:[1,0]
	v_mov_b32_e32 v99, v97
	v_pk_add_f32 v[86:87], v[100:101], v[86:87]
	v_mul_f32_e32 v96, v69, v69
	v_pk_add_f32 v[84:85], v[84:85], v[98:99]
	v_mul_f32_e32 v98, v71, v71
	v_mul_f32_e32 v102, v60, v60
	v_mul_f32_e32 v103, v61, v61
	v_mul_f32_e32 v108, v62, v62
	v_mul_f32_e32 v109, v63, v63
	v_pk_fma_f32 v[96:97], v[68:69], v[68:69], v[96:97] op_sel_hi:[1,1,0]
	v_pk_fma_f32 v[98:99], v[70:71], v[70:71], v[98:99] op_sel_hi:[1,1,0]
	v_pk_add_f32 v[86:87], v[86:87], v[86:87] op_sel:[0,1] op_sel_hi:[1,0]
	v_pk_add_f32 v[84:85], v[84:85], v[84:85] op_sel:[0,1] op_sel_hi:[1,0]
	v_mov_b32_e32 v97, v108
	v_mov_b32_e32 v99, v109
	v_mov_b32_e32 v87, v102
	v_mov_b32_e32 v85, v103
	v_pk_add_f32 v[96:97], v[96:97], v[98:99]
	v_pk_add_f32 v[84:85], v[86:87], v[84:85]
	v_pk_mul_f32 v[86:87], v[14:15], v[14:15]
	v_pk_add_f32 v[84:85], v[84:85], v[96:97]
	v_pk_mul_f32 v[96:97], v[12:13], v[12:13]
	v_pk_mul_f32 v[98:99], v[10:11], v[10:11]
	v_pk_mul_f32 v[100:101], v[8:9], v[8:9]
	v_pk_mov_b32 v[102:103], v[96:97], v[86:87] op_sel:[1,0]
	v_mov_b32_e32 v97, v87
	v_pk_mov_b32 v[108:109], v[100:101], v[98:99] op_sel:[1,0]
	v_mov_b32_e32 v101, v99
	v_mov_b32_e32 v99, v94
	v_mov_b32_e32 v98, v84
	v_mov_b32_e32 v94, v85
	v_pk_add_f32 v[96:97], v[102:103], v[96:97]
	v_mul_f32_e32 v103, v2, v2
	v_mul_f32_e32 v102, v5, v5
	v_pk_add_f32 v[100:101], v[108:109], v[100:101]
	v_pk_fma_f32 v[108:109], v[4:5], v[4:5], v[102:103] op_sel_hi:[1, 1, 0]
	v_mul_f32_e32 v110, v3, v3
	v_mov_b32_e32 v109, v103
	v_pk_add_f32 v[102:103], v[98:99], v[94:95]
	v_mul_f32_e32 v94, v7, v7
	v_pk_fma_f32 v[94:95], v[6:7], v[6:7], v[94:95] op_sel_hi:[1, 1, 0]
	v_mul_f32_e32 v98, v0, v0
	v_mov_b32_e32 v95, v110
	v_pk_add_f32 v[108:109], v[108:109], v[94:95]
	v_mul_f32_e32 v99, v1, v1
	v_pk_add_f32 v[94:95], v[96:97], v[96:97] op_sel:[0, 1] op_sel_hi:[1, 0]
	v_pk_add_f32 v[96:97], v[100:101], v[100:101] op_sel:[0, 1] op_sel_hi:[1, 0]
	v_mov_b32_e32 v95, v98
	v_mov_b32_e32 v97, v99
	v_pk_add_f32 v[98:99], v[106:107], 1.0 op_sel_hi:[1, 0]
	v_pk_add_f32 v[100:101], v[104:105], 1.0 op_sel_hi:[1, 0]
	v_pk_add_f32 v[104:105], v[128:129], 1.0 op_sel_hi:[1, 0]
	v_pk_add_f32 v[106:107], v[126:127], 1.0 op_sel_hi:[1, 0]
	v_pk_add_f32 v[110:111], v[94:95], v[96:97]
	v_pk_mul_f32 v[78:79], v[78:79], v[104:105]
	v_pk_mul_f32 v[76:77], v[76:77], v[106:107]
	v_pk_mul_f32 v[112:113], v[30:31], v[30:31]
	v_pk_mul_f32 v[104:105], v[28:29], v[28:29]
	v_pk_mul_f32 v[106:107], v[24:25], v[24:25]
	v_pk_add_f32 v[108:109], v[110:111], v[108:109]
	v_pk_mov_b32 v[110:111], v[104:105], v[112:113] op_sel:[1, 0]
	v_mov_b32_e32 v105, v113
	v_pk_add_f32 v[94:95], v[34:35], 1.0 op_sel_hi:[1, 0]
	v_pk_add_f32 v[96:97], v[32:33], 1.0 op_sel_hi:[1, 0]
	v_pk_mul_f32 v[94:95], v[38:39], v[94:95]
	v_pk_mul_f32 v[96:97], v[36:37], v[96:97]
	v_pk_mul_f32 v[98:99], v[42:43], v[98:99]
	v_pk_mul_f32 v[100:101], v[40:41], v[100:101]
	v_mul_f32_e32 v125, v18, v18
	v_mul_f32_e32 v126, v19, v19
	v_pk_add_f32 v[84:85], v[130:131], 1.0 op_sel_hi:[1, 0]
	s_nop 0
	v_pk_mul_f32 v[80:81], v[80:81], v[84:85]
	v_pk_mul_f32 v[84:85], v[26:27], v[26:27]
	v_pk_add_f32 v[86:87], v[132:133], 1.0 op_sel_hi:[1, 0]
	v_pk_mov_b32 v[112:113], v[106:107], v[84:85] op_sel:[1, 0]
	v_mov_b32_e32 v107, v85
	v_pk_mul_f32 v[82:83], v[82:83], v[86:87]
	v_pk_add_f32 v[106:107], v[112:113], v[106:107]
	v_mul_f32_e32 v112, v16, v16
	v_pk_add_f32 v[106:107], v[106:107], v[106:107] op_sel:[0, 1] op_sel_hi:[1, 0]
	s_nop 1
	v_add_f32_dpp v84, v102, v102 quad_perm:[1, 0, 3, 2] row_mask:0xf bank_mask:0xf
	v_add_f32_dpp v85, v103, v103 quad_perm:[1, 0, 3, 2] row_mask:0xf bank_mask:0xf
	s_nop 1
	v_add_f32_dpp v84, v84, v84 quad_perm:[2, 3, 0, 1] row_mask:0xf bank_mask:0xf
	v_add_f32_dpp v85, v85, v85 quad_perm:[2, 3, 0, 1] row_mask:0xf bank_mask:0xf
	s_nop 1
	v_add_f32_dpp v84, v84, v84 row_half_mirror row_mask:0xf bank_mask:0xf
	v_add_f32_dpp v85, v85, v85 row_half_mirror row_mask:0xf bank_mask:0xf
	s_nop 1
	v_add_f32_dpp v84, v84, v84 row_mirror row_mask:0xf bank_mask:0xf
	v_add_f32_dpp v85, v85, v85 row_mirror row_mask:0xf bank_mask:0xf
	v_mov_b32_e32 v86, v84
	v_mov_b32_e32 v87, v85
	s_nop 1
	v_permlane16_swap_b32_e32 v84, v86
	v_permlane16_swap_b32_e32 v85, v87
	v_pk_add_f32 v[84:85], v[84:85], v[86:87]
	v_mov_b32_e32 v86, v84
	v_mov_b32_e32 v87, v85
	s_nop 1
	v_permlane32_swap_b32_e32 v84, v86
	v_permlane32_swap_b32_e32 v85, v87
	v_pk_add_f32 v[84:85], v[84:85], v[86:87]
	s_nop 0
	v_pk_fma_f32 v[84:85], v[84:85], s[20:21], v[92:93] op_sel_hi:[1, 0, 0]
	s_nop 0
	v_mul_f32_e32 v86, 0x4b800000, v85
	v_cmp_gt_f32_e64 s[0:1], s18, v85
	v_mul_f32_e32 v87, 0x4b800000, v84
	v_cmp_gt_f32_e32 vcc, s18, v84
	v_cndmask_b32_e64 v85, v85, v86, s[0:1]
	v_rsq_f32_e32 v85, v85
	v_cndmask_b32_e32 v84, v84, v87, vcc
	v_rsq_f32_e32 v102, v84
	v_mul_f32_e32 v84, 0x45800000, v85
	v_cndmask_b32_e64 v86, v85, v84, s[0:1]
	v_pk_mul_f32 v[84:85], v[50:51], v[86:87] op_sel_hi:[1, 0]
	v_pk_mul_f32 v[50:51], v[52:53], v[86:87] op_sel_hi:[1, 0]
	v_pk_mul_f32 v[52:53], v[44:45], v[86:87] op_sel_hi:[1, 0]
	v_mul_f32_e32 v44, 0x45800000, v102
	v_cndmask_b32_e32 v44, v102, v44, vcc
	v_pk_mul_f32 v[56:57], v[56:57], v[86:87] op_sel_hi:[1, 0]
	v_pk_mul_f32 v[58:59], v[58:59], v[86:87] op_sel_hi:[1, 0]
	v_pk_mul_f32 v[48:49], v[48:49], v[86:87] op_sel_hi:[1, 0]
	v_pk_mul_f32 v[54:55], v[54:55], v[86:87] op_sel_hi:[1, 0]
	v_pk_mul_f32 v[86:87], v[46:47], v[86:87] op_sel_hi:[1, 0]
	v_pk_mul_f32 v[72:73], v[72:73], v[44:45] op_sel_hi:[1, 0]
	v_pk_mul_f32 v[74:75], v[74:75], v[44:45] op_sel_hi:[1, 0]
	v_pk_mul_f32 v[64:65], v[64:65], v[44:45] op_sel_hi:[1, 0]
	v_pk_mul_f32 v[102:103], v[66:67], v[44:45] op_sel_hi:[1, 0]
	v_pk_mul_f32 v[66:67], v[68:69], v[44:45] op_sel_hi:[1, 0]
	v_pk_mul_f32 v[68:69], v[70:71], v[44:45] op_sel_hi:[1, 0]
	v_pk_mul_f32 v[60:61], v[60:61], v[44:45] op_sel_hi:[1, 0]
	v_pk_mul_f32 v[62:63], v[62:63], v[44:45] op_sel_hi:[1, 0]
	v_pk_add_f32 v[70:71], v[110:111], v[104:105]
	v_mul_f32_e32 v104, v21, v21
	v_mul_f32_e32 v110, v23, v23
	v_pk_add_f32 v[70:71], v[70:71], v[70:71] op_sel:[0, 1] op_sel_hi:[1, 0]
	v_pk_fma_f32 v[104:105], v[20:21], v[20:21], v[104:105] op_sel_hi:[1, 1, 0]
	v_pk_fma_f32 v[110:111], v[22:23], v[22:23], v[110:111] op_sel_hi:[1, 1, 0]
	v_mov_b32_e32 v71, v112
	v_mul_f32_e32 v112, v17, v17
	v_mov_b32_e32 v105, v125
	v_mov_b32_e32 v111, v126
	v_mov_b32_e32 v107, v112
	v_pk_add_f32 v[110:111], v[104:105], v[110:111]
	v_pk_add_f32 v[70:71], v[70:71], v[106:107]
	s_lshl_b64 s[12:13], s[4:5], 11
	v_pk_add_f32 v[70:71], v[70:71], v[110:111]
	v_mov_b32_e32 v111, v108
	v_mov_b32_e32 v110, v70
	v_mov_b32_e32 v108, v71
	v_pk_add_f32 v[108:109], v[110:111], v[108:109]
	s_lshl_b64 s[0:1], s[2:3], 11
	v_pk_fma_f32 v[58:59], v[94:95], v[58:59], v[136:137]
	v_pk_fma_f32 v[56:57], v[96:97], v[56:57], v[134:135]
	v_lshl_add_u64 v[104:105], v[88:89], 0, s[12:13]
	s_nop 1
	v_add_f32_dpp v108, v108, v108 quad_perm:[1, 0, 3, 2] row_mask:0xf bank_mask:0xf
	v_add_f32_dpp v109, v109, v109 quad_perm:[1, 0, 3, 2] row_mask:0xf bank_mask:0xf
	v_pk_fma_f32 v[48:49], v[100:101], v[48:49], v[138:139]
	v_cvt_pk_bf16_f32 v56, v56, v57
	v_cvt_pk_bf16_f32 v57, v58, v59
	v_pk_fma_f32 v[50:51], v[50:51], v[76:77], v[142:143]
	s_nop 1
	v_add_f32_dpp v108, v108, v108 quad_perm:[2, 3, 0, 1] row_mask:0xf bank_mask:0xf
	v_add_f32_dpp v109, v109, v109 quad_perm:[2, 3, 0, 1] row_mask:0xf bank_mask:0xf
	global_store_dwordx2 v[104:105], v[56:57], off
	v_cvt_pk_bf16_f32 v48, v48, v49
	v_pk_fma_f32 v[84:85], v[98:99], v[84:85], v[140:141]
	v_pk_fma_f32 v[54:55], v[54:55], v[78:79], v[144:145]
	s_nop 1
	v_add_f32_dpp v108, v108, v108 row_half_mirror row_mask:0xf bank_mask:0xf
	v_add_f32_dpp v109, v109, v109 row_half_mirror row_mask:0xf bank_mask:0xf
	v_cvt_pk_bf16_f32 v49, v84, v85
	global_store_dwordx2 v[104:105], v[48:49], off offset:512
	v_cvt_pk_bf16_f32 v48, v50, v51
	v_cvt_pk_bf16_f32 v49, v54, v55
	s_nop 1
	v_add_f32_dpp v108, v108, v108 row_mirror row_mask:0xf bank_mask:0xf
	v_add_f32_dpp v109, v109, v109 row_mirror row_mask:0xf bank_mask:0xf
	global_store_dwordx2 v[104:105], v[48:49], off offset:1024
	v_lshl_add_u64 v[106:107], v[88:89], 0, s[8:9]
	v_pk_fma_f32 v[74:75], v[94:95], v[74:75], v[136:137]
	v_pk_fma_f32 v[72:73], v[96:97], v[72:73], v[134:135]
	v_mov_b32_e32 v110, v108
	v_mov_b32_e32 v111, v109
	s_nop 1
	v_permlane16_swap_b32_e32 v108, v110
	v_permlane16_swap_b32_e32 v109, v111
	v_pk_add_f32 v[108:109], v[108:109], v[110:111]
	s_lshl_b64 s[4:5], s[10:11], 11
	v_pk_fma_f32 v[102:103], v[98:99], v[102:103], v[140:141]
	v_pk_fma_f32 v[64:65], v[100:101], v[64:65], v[138:139]
	v_lshl_add_u64 v[70:71], v[88:89], 0, s[4:5]
	v_mov_b32_e32 v110, v108
	v_mov_b32_e32 v111, v109
	s_nop 1
	v_permlane32_swap_b32_e32 v108, v110
	v_permlane32_swap_b32_e32 v109, v111
	v_pk_add_f32 v[110:111], v[108:109], v[110:111]
	v_lshl_add_u64 v[108:109], v[88:89], 0, s[0:1]
	v_pk_fma_f32 v[92:93], v[110:111], s[20:21], v[92:93] op_sel_hi:[1, 0, 0]
	v_pk_fma_f32 v[68:69], v[78:79], v[68:69], v[144:145]
	v_mul_f32_e32 v58, 0x4b800000, v93
	v_cmp_gt_f32_e64 s[0:1], s18, v93
	v_mul_f32_e32 v59, 0x4b800000, v92
	v_cmp_gt_f32_e32 vcc, s18, v92
	v_cndmask_b32_e64 v56, v93, v58, s[0:1]
	v_rsq_f32_e32 v50, v56
	v_cndmask_b32_e32 v57, v92, v59, vcc
	v_rsq_f32_e32 v51, v57
	v_pk_fma_f32 v[66:67], v[76:77], v[66:67], v[142:143]
	s_add_i32 s2, s2, s24
	s_cmpk_lt_i32 s14, 0x2400
	s_waitcnt vmcnt(3)
	v_pk_fma_f32 v[52:53], v[52:53], v[80:81], v[146:147]
	v_pk_fma_f32 v[86:87], v[86:87], v[82:83], v[148:149]
	v_cvt_pk_bf16_f32 v48, v52, v53
	v_mul_f32_e32 v52, 0x45800000, v50
	v_cvt_pk_bf16_f32 v49, v86, v87
	global_store_dwordx2 v[104:105], v[48:49], off offset:1536
	v_cvt_pk_bf16_f32 v48, v72, v73
	v_cvt_pk_bf16_f32 v49, v74, v75
	v_cndmask_b32_e64 v50, v50, v52, s[0:1]
	global_store_dwordx2 v[106:107], v[48:49], off
	v_cvt_pk_bf16_f32 v48, v64, v65
	v_cvt_pk_bf16_f32 v49, v102, v103
	v_mul_f32_e32 v53, 0x45800000, v51
	v_pk_mul_f32 v[12:13], v[12:13], v[50:51] op_sel_hi:[1, 0]
	v_pk_mul_f32 v[8:9], v[8:9], v[50:51] op_sel_hi:[1, 0]
	v_pk_mul_f32 v[4:5], v[4:5], v[50:51] op_sel_hi:[1, 0]
	v_pk_mul_f32 v[0:1], v[0:1], v[50:51] op_sel_hi:[1, 0]
	global_store_dwordx2 v[106:107], v[48:49], off offset:512
	v_cvt_pk_bf16_f32 v48, v66, v67
	v_cvt_pk_bf16_f32 v49, v68, v69
	v_cndmask_b32_e32 v52, v51, v53, vcc
	v_pk_mul_f32 v[14:15], v[14:15], v[50:51] op_sel_hi:[1, 0]
	v_pk_mul_f32 v[10:11], v[10:11], v[50:51] op_sel_hi:[1, 0]
	v_pk_mul_f32 v[6:7], v[6:7], v[50:51] op_sel_hi:[1, 0]
	v_pk_mul_f32 v[2:3], v[2:3], v[50:51] op_sel_hi:[1, 0]
	v_pk_fma_f32 v[12:13], v[96:97], v[12:13], v[134:135]
	v_pk_fma_f32 v[8:9], v[100:101], v[8:9], v[138:139]
	v_pk_fma_f32 v[4:5], v[76:77], v[4:5], v[142:143]
	v_pk_fma_f32 v[0:1], v[0:1], v[80:81], v[146:147]
	v_pk_fma_f32 v[62:63], v[62:63], v[82:83], v[148:149]
	v_pk_fma_f32 v[60:61], v[60:61], v[80:81], v[146:147]
	global_store_dwordx2 v[106:107], v[48:49], off offset:1024
	v_cvt_pk_bf16_f32 v48, v60, v61
	v_cvt_pk_bf16_f32 v49, v62, v63
	global_store_dwordx2 v[106:107], v[48:49], off offset:1536
	v_pk_mul_f32 v[28:29], v[28:29], v[52:53] op_sel_hi:[1, 0]
	v_pk_mul_f32 v[30:31], v[30:31], v[52:53] op_sel_hi:[1, 0]
	v_pk_fma_f32 v[14:15], v[94:95], v[14:15], v[136:137]
	v_pk_fma_f32 v[10:11], v[98:99], v[10:11], v[140:141]
	v_pk_fma_f32 v[6:7], v[78:79], v[6:7], v[144:145]
	v_pk_fma_f32 v[2:3], v[2:3], v[82:83], v[148:149]
	v_cvt_pk_bf16_f32 v12, v12, v13
	v_cvt_pk_bf16_f32 v13, v14, v15
	global_store_dwordx2 v[70:71], v[12:13], off
	v_cvt_pk_bf16_f32 v8, v8, v9
	v_cvt_pk_bf16_f32 v9, v10, v11
	global_store_dwordx2 v[70:71], v[8:9], off offset:512
	v_cvt_pk_bf16_f32 v4, v4, v5
	v_cvt_pk_bf16_f32 v5, v6, v7
	global_store_dwordx2 v[70:71], v[4:5], off offset:1024
	v_cvt_pk_bf16_f32 v0, v0, v1
	v_cvt_pk_bf16_f32 v1, v2, v3
	v_pk_mul_f32 v[24:25], v[24:25], v[52:53] op_sel_hi:[1, 0]
	v_pk_mul_f32 v[26:27], v[26:27], v[52:53] op_sel_hi:[1, 0]
	v_pk_fma_f32 v[30:31], v[94:95], v[30:31], v[136:137]
	v_pk_fma_f32 v[28:29], v[96:97], v[28:29], v[134:135]
	global_store_dwordx2 v[70:71], v[0:1], off offset:1536
	v_cvt_pk_bf16_f32 v0, v28, v29
	v_cvt_pk_bf16_f32 v1, v30, v31
	v_pk_mul_f32 v[20:21], v[20:21], v[52:53] op_sel_hi:[1, 0]
	v_pk_mul_f32 v[22:23], v[22:23], v[52:53] op_sel_hi:[1, 0]
	v_pk_fma_f32 v[26:27], v[98:99], v[26:27], v[140:141]
	v_pk_fma_f32 v[24:25], v[100:101], v[24:25], v[138:139]
	global_store_dwordx2 v[108:109], v[0:1], off
	v_cvt_pk_bf16_f32 v0, v24, v25
	v_cvt_pk_bf16_f32 v1, v26, v27
	v_pk_mul_f32 v[16:17], v[16:17], v[52:53] op_sel_hi:[1, 0]
	v_pk_mul_f32 v[18:19], v[18:19], v[52:53] op_sel_hi:[1, 0]
	v_pk_fma_f32 v[22:23], v[78:79], v[22:23], v[144:145]
	v_pk_fma_f32 v[20:21], v[76:77], v[20:21], v[142:143]
	global_store_dwordx2 v[108:109], v[0:1], off offset:512
	v_cvt_pk_bf16_f32 v0, v20, v21
	v_cvt_pk_bf16_f32 v1, v22, v23
	v_pk_fma_f32 v[18:19], v[18:19], v[82:83], v[148:149]
	v_pk_fma_f32 v[16:17], v[16:17], v[80:81], v[146:147]
	global_store_dwordx2 v[108:109], v[0:1], off offset:1024
	v_cvt_pk_bf16_f32 v0, v16, v17
	v_cvt_pk_bf16_f32 v1, v18, v19
	global_store_dwordx2 v[108:109], v[0:1], off offset:1536
	s_cbranch_scc1 .LBB0_492
